# FF2 residual epilogue: all eight row groups' residual lines touched (dummy dword loads, own address arithmetic) before the groups are processed one after another
# baseline (speedup 1.0000x reference)
;     __device__ __forceinline__ void operator()(const f32x4 (&acc)[2][2][4][2], const Unit& u, int wr, int wc, int fr, int fq) const {
;         const int row0 = u.pm * BM + wr * 64 + fr, col0 = u.pn * BM + wc * 32 + 4 * fq;
; #pragma unroll
;         for (int ai = 0; ai < 2; ++ai)
; #pragma unroll
;             for (int m = 0; m < 4; ++m) { const int row = row0 + ai * HALF + m * 16;
;                 if (row < M) { float* hp = hrow(*p, row) + col0; const float* sp = FIRST ? xrow(*p, row) + col0 : hp;
; #pragma unroll
;                     for (int bj = 0; bj < 2; ++bj)
; #pragma unroll
;                         for (int n = 0; n < 2; ++n) { f32x4 h = *(const f32x4*)(sp + bj * HALF + n * 16); h += acc[ai][bj][m][n]; *(f32x4*)(hp + bj * HALF + n * 16) = h; } } }
.LBB0_2354:
	v_lshl_add_u32 v169, s16, 8, v131
	v_lshl_or_b32 v158, s94, 8, v168
	v_ashrrev_i32_e32 v159, 31, v158
	v_readlane_b32 s98, v253, 2
	v_readlane_b32 s99, v253, 3
	v_mov_b32_e32 v238, s14
	v_mov_b32_e32 v239, s15
	s_nop 0
	v_mov_b32_e32 v240, s98
	v_mov_b32_e32 v241, s99
	v_mov_b32_e32 v230, v169
	v_min_i32_e32 v230, 0x807f, v230
	v_mul_hi_i32 v231, v230, s23
	v_lshrrev_b32_e32 v232, 31, v231
	v_ashrrev_i32_e32 v231, 11, v231
	v_add_u32_e32 v231, v231, v232
	v_mad_i32_i24 v232, v231, s24, v230
	v_cmp_lt_i32_e32 vcc, 15, v232
	v_add_u32_e32 v233, -16, v232
	v_lshl_add_u32 v234, v231, 4, v232
	v_lshlrev_b32_e32 v235, 24, v231
	v_lshl_add_u32 v233, v233, 12, v235
	v_lshlrev_b32_e32 v234, 12, v234
	v_cndmask_b32_e32 v236, v234, v233, vcc
	v_cndmask_b32_e32 v242, v238, v240, vcc
	v_cndmask_b32_e32 v243, v239, v241, vcc
	v_mov_b32_e32 v237, 0
	v_lshl_add_u64 v[236:237], v[242:243], 0, v[236:237]
	v_lshl_add_u64 v[236:237], v[158:159], 2, v[236:237]
	global_load_dword v244, v[236:237], off
	global_load_dword v244, v[236:237], off offset:64
	global_load_dword v244, v[236:237], off offset:512
	global_load_dword v244, v[236:237], off offset:576
	v_add_u32_e32 v230, 0x10, v169
	v_min_i32_e32 v230, 0x807f, v230
	v_mul_hi_i32 v231, v230, s23
	v_lshrrev_b32_e32 v232, 31, v231
	v_ashrrev_i32_e32 v231, 11, v231
	v_add_u32_e32 v231, v231, v232
	v_mad_i32_i24 v232, v231, s24, v230
	v_cmp_lt_i32_e32 vcc, 15, v232
	v_add_u32_e32 v233, -16, v232
	v_lshl_add_u32 v234, v231, 4, v232
	v_lshlrev_b32_e32 v235, 24, v231
	v_lshl_add_u32 v233, v233, 12, v235
	v_lshlrev_b32_e32 v234, 12, v234
	v_cndmask_b32_e32 v236, v234, v233, vcc
	v_cndmask_b32_e32 v242, v238, v240, vcc
	v_cndmask_b32_e32 v243, v239, v241, vcc
	v_mov_b32_e32 v237, 0
	v_lshl_add_u64 v[236:237], v[242:243], 0, v[236:237]
	v_lshl_add_u64 v[236:237], v[158:159], 2, v[236:237]
	global_load_dword v244, v[236:237], off
	global_load_dword v244, v[236:237], off offset:64
	global_load_dword v244, v[236:237], off offset:512
	global_load_dword v244, v[236:237], off offset:576
	v_add_u32_e32 v230, 0x20, v169
	v_min_i32_e32 v230, 0x807f, v230
	v_mul_hi_i32 v231, v230, s23
	v_lshrrev_b32_e32 v232, 31, v231
	v_ashrrev_i32_e32 v231, 11, v231
	v_add_u32_e32 v231, v231, v232
	v_mad_i32_i24 v232, v231, s24, v230
	v_cmp_lt_i32_e32 vcc, 15, v232
	v_add_u32_e32 v233, -16, v232
	v_lshl_add_u32 v234, v231, 4, v232
	v_lshlrev_b32_e32 v235, 24, v231
	v_lshl_add_u32 v233, v233, 12, v235
	v_lshlrev_b32_e32 v234, 12, v234
	v_cndmask_b32_e32 v236, v234, v233, vcc
	v_cndmask_b32_e32 v242, v238, v240, vcc
	v_cndmask_b32_e32 v243, v239, v241, vcc
	v_mov_b32_e32 v237, 0
	v_lshl_add_u64 v[236:237], v[242:243], 0, v[236:237]
	v_lshl_add_u64 v[236:237], v[158:159], 2, v[236:237]
	global_load_dword v244, v[236:237], off
	global_load_dword v244, v[236:237], off offset:64
	global_load_dword v244, v[236:237], off offset:512
	global_load_dword v244, v[236:237], off offset:576
	v_add_u32_e32 v230, 0x30, v169
	v_min_i32_e32 v230, 0x807f, v230
	v_mul_hi_i32 v231, v230, s23
	v_lshrrev_b32_e32 v232, 31, v231
	v_ashrrev_i32_e32 v231, 11, v231
	v_add_u32_e32 v231, v231, v232
	v_mad_i32_i24 v232, v231, s24, v230
	v_cmp_lt_i32_e32 vcc, 15, v232
	v_add_u32_e32 v233, -16, v232
	v_lshl_add_u32 v234, v231, 4, v232
	v_lshlrev_b32_e32 v235, 24, v231
	v_lshl_add_u32 v233, v233, 12, v235
	v_lshlrev_b32_e32 v234, 12, v234
	v_cndmask_b32_e32 v236, v234, v233, vcc
	v_cndmask_b32_e32 v242, v238, v240, vcc
	v_cndmask_b32_e32 v243, v239, v241, vcc
	v_mov_b32_e32 v237, 0
	v_lshl_add_u64 v[236:237], v[242:243], 0, v[236:237]
	v_lshl_add_u64 v[236:237], v[158:159], 2, v[236:237]
	global_load_dword v244, v[236:237], off
	global_load_dword v244, v[236:237], off offset:64
	global_load_dword v244, v[236:237], off offset:512
	global_load_dword v244, v[236:237], off offset:576
	v_add_u32_e32 v230, 0x80, v169
	v_min_i32_e32 v230, 0x807f, v230
	v_mul_hi_i32 v231, v230, s23
	v_lshrrev_b32_e32 v232, 31, v231
	v_ashrrev_i32_e32 v231, 11, v231
	v_add_u32_e32 v231, v231, v232
;     __device__ __forceinline__ void operator()(const f32x4 (&acc)[2][2][4][2], const Unit& u, int wr, int wc, int fr, int fq) const {
;         const int row0 = u.pm * BM + wr * 64 + fr, col0 = u.pn * BM + wc * 32 + 4 * fq;
; #pragma unroll
;         for (int ai = 0; ai < 2; ++ai)
; #pragma unroll
;             for (int m = 0; m < 4; ++m) { const int row = row0 + ai * HALF + m * 16;
;                 if (row < M) { float* hp = hrow(*p, row) + col0; const float* sp = FIRST ? xrow(*p, row) + col0 : hp;
; #pragma unroll
;                     for (int bj = 0; bj < 2; ++bj)
; #pragma unroll
;                         for (int n = 0; n < 2; ++n) { f32x4 h = *(const f32x4*)(sp + bj * HALF + n * 16); h += acc[ai][bj][m][n]; *(f32x4*)(hp + bj * HALF + n * 16) = h; } } }
	v_mad_i32_i24 v232, v231, s24, v230
	v_cmp_lt_i32_e32 vcc, 15, v232
	v_add_u32_e32 v233, -16, v232
	v_lshl_add_u32 v234, v231, 4, v232
	v_lshlrev_b32_e32 v235, 24, v231
	v_lshl_add_u32 v233, v233, 12, v235
	v_lshlrev_b32_e32 v234, 12, v234
	v_cndmask_b32_e32 v236, v234, v233, vcc
	v_cndmask_b32_e32 v242, v238, v240, vcc
	v_cndmask_b32_e32 v243, v239, v241, vcc
	v_mov_b32_e32 v237, 0
	v_lshl_add_u64 v[236:237], v[242:243], 0, v[236:237]
	v_lshl_add_u64 v[236:237], v[158:159], 2, v[236:237]
	global_load_dword v244, v[236:237], off
	global_load_dword v244, v[236:237], off offset:64
	global_load_dword v244, v[236:237], off offset:512
	global_load_dword v244, v[236:237], off offset:576
	v_add_u32_e32 v230, 0x90, v169
	v_min_i32_e32 v230, 0x807f, v230
	v_mul_hi_i32 v231, v230, s23
	v_lshrrev_b32_e32 v232, 31, v231
	v_ashrrev_i32_e32 v231, 11, v231
	v_add_u32_e32 v231, v231, v232
	v_mad_i32_i24 v232, v231, s24, v230
	v_cmp_lt_i32_e32 vcc, 15, v232
	v_add_u32_e32 v233, -16, v232
	v_lshl_add_u32 v234, v231, 4, v232
	v_lshlrev_b32_e32 v235, 24, v231
	v_lshl_add_u32 v233, v233, 12, v235
	v_lshlrev_b32_e32 v234, 12, v234
	v_cndmask_b32_e32 v236, v234, v233, vcc
	v_cndmask_b32_e32 v242, v238, v240, vcc
	v_cndmask_b32_e32 v243, v239, v241, vcc
	v_mov_b32_e32 v237, 0
	v_lshl_add_u64 v[236:237], v[242:243], 0, v[236:237]
	v_lshl_add_u64 v[236:237], v[158:159], 2, v[236:237]
	global_load_dword v244, v[236:237], off
	global_load_dword v244, v[236:237], off offset:64
	global_load_dword v244, v[236:237], off offset:512
	global_load_dword v244, v[236:237], off offset:576
	v_add_u32_e32 v230, 0xa0, v169
	v_min_i32_e32 v230, 0x807f, v230
	v_mul_hi_i32 v231, v230, s23
	v_lshrrev_b32_e32 v232, 31, v231
	v_ashrrev_i32_e32 v231, 11, v231
	v_add_u32_e32 v231, v231, v232
	v_mad_i32_i24 v232, v231, s24, v230
	v_cmp_lt_i32_e32 vcc, 15, v232
	v_add_u32_e32 v233, -16, v232
	v_lshl_add_u32 v234, v231, 4, v232
	v_lshlrev_b32_e32 v235, 24, v231
	v_lshl_add_u32 v233, v233, 12, v235
	v_lshlrev_b32_e32 v234, 12, v234
	v_cndmask_b32_e32 v236, v234, v233, vcc
	v_cndmask_b32_e32 v242, v238, v240, vcc
	v_cndmask_b32_e32 v243, v239, v241, vcc
	v_mov_b32_e32 v237, 0
	v_lshl_add_u64 v[236:237], v[242:243], 0, v[236:237]
	v_lshl_add_u64 v[236:237], v[158:159], 2, v[236:237]
	global_load_dword v244, v[236:237], off
	global_load_dword v244, v[236:237], off offset:64
	global_load_dword v244, v[236:237], off offset:512
	global_load_dword v244, v[236:237], off offset:576
	v_add_u32_e32 v230, 0xb0, v169
	v_min_i32_e32 v230, 0x807f, v230
	v_mul_hi_i32 v231, v230, s23
	v_lshrrev_b32_e32 v232, 31, v231
	v_ashrrev_i32_e32 v231, 11, v231
	v_add_u32_e32 v231, v231, v232
	v_mad_i32_i24 v232, v231, s24, v230
	v_cmp_lt_i32_e32 vcc, 15, v232
	v_add_u32_e32 v233, -16, v232
	v_lshl_add_u32 v234, v231, 4, v232
	v_lshlrev_b32_e32 v235, 24, v231
	v_lshl_add_u32 v233, v233, 12, v235
	v_lshlrev_b32_e32 v234, 12, v234
	v_cndmask_b32_e32 v236, v234, v233, vcc
	v_cndmask_b32_e32 v242, v238, v240, vcc
	v_cndmask_b32_e32 v243, v239, v241, vcc
	v_mov_b32_e32 v237, 0
	v_lshl_add_u64 v[236:237], v[242:243], 0, v[236:237]
	v_lshl_add_u64 v[236:237], v[158:159], 2, v[236:237]
	global_load_dword v244, v[236:237], off
	global_load_dword v244, v[236:237], off offset:64
	global_load_dword v244, v[236:237], off offset:512
	global_load_dword v244, v[236:237], off offset:576
	v_cmp_gt_i32_e32 vcc, s22, v169
	s_and_saveexec_b64 s[16:17], vcc
	s_cbranch_execz .LBB0_2360
	v_mul_hi_i32 v160, v169, s23
	v_lshrrev_b32_e32 v161, 31, v160
	v_ashrrev_i32_e32 v160, 11, v160
	v_add_u32_e32 v162, v160, v161
	v_mad_i32_i24 v170, v162, s24, v169
	v_cmp_lt_i32_e32 vcc, 15, v170
	s_and_saveexec_b64 s[18:19], vcc
	s_xor_b64 s[18:19], exec, s[18:19]
	s_cbranch_execz .LBB0_2357
	v_ashrrev_i32_e32 v163, 31, v162
	v_readlane_b32 s48, v253, 2
	v_lshlrev_b64 v[162:163], 24, v[162:163]
	v_readlane_b32 s49, v253, 3
	v_add_u32_e32 v160, -16, v170
	v_mov_b32_e32 v161, v130
	v_readlane_b32 s50, v253, 4
	v_readlane_b32 s51, v253, 5
	v_lshl_add_u64 v[164:165], s[48:49], 0, v[162:163]
